# first barrier too: P0 stores all write-through, no L2 write-back before arrival
# speedup vs baseline: 1.0370x; 1.0089x over previous
; __global__ void __launch_bounds__(512, 2) hymba_fwd(Params p) {
;     ...
;     if (c == 0) for (int i = threadIdx.x; i < 2176; i += 512) xb.bar[1024 + i] = 0u;
.LBB0_3:
	s_mov_b32 s13, s12
	s_or_b64 s[14:15], s[12:13], s[8:9]
	v_cmp_le_u32_e64 s[4:5], s15, v1
	v_cmp_le_u32_e32 vcc, s14, v2
	s_and_saveexec_b64 s[14:15], vcc
	s_cbranch_execz .LBB0_5
	v_readlane_b32 s16, v253, 0
	v_mov_b32_e32 v4, v6
	v_readlane_b32 s17, v253, 1
	s_nop 1
	v_lshl_add_u64 v[8:9], v[4:5], 2, s[16:17]
	v_add_co_u32_e32 v8, vcc, 0x1000, v8
	s_nop 1
	v_addc_co_u32_e32 v9, vcc, 0, v9, vcc
	global_store_dword v[8:9], v5, off sc0 sc1
.LBB0_5:
	s_or_b64 exec, exec, s[14:15]
	s_and_saveexec_b64 s[14:15], s[4:5]
	s_cbranch_execz .LBB0_2
	v_readlane_b32 s4, v253, 0
	v_mov_b32_e32 v4, v7
	v_readlane_b32 s5, v253, 1
	s_nop 1
	v_lshl_add_u64 v[8:9], v[4:5], 2, s[4:5]
	v_add_co_u32_e32 v8, vcc, 0x1000, v8
	s_nop 1
	v_addc_co_u32_e32 v9, vcc, 0, v9, vcc
	global_store_dword v[8:9], v5, off sc0 sc1
	s_branch .LBB0_2

; __device__ __forceinline__ unsigned xb_xcc_id() { return (unsigned)__builtin_amdgcn_s_getreg((3 << 11) | 20) & 0xFu; }
; __global__ void __launch_bounds__(512, 2) hymba_fwd(Params p) {
;     ...
;     XB xb; xb.bar = (unsigned*)(ws + OFF_BAR); xb.x = xb_xcc_id();
;     if (c == 0) for (int i = threadIdx.x; i < 2176; i += 512) xb.bar[1024 + i] = 0u;
;     if (threadIdx.x == 0) xb.bar[3200 + c] = xb.x;
.LBB0_8:
	s_and_b32 s89, s3, 15
	v_cmp_eq_u32_e64 s[8:9], 0, v132
	s_mov_b64 s[4:5], exec
	s_nop 0
	v_writelane_b32 v253, s8, 2
	s_nop 1
	v_writelane_b32 v253, s9, 3
	s_and_b64 s[8:9], s[4:5], s[8:9]
	s_mov_b64 exec, s[8:9]
	s_cbranch_execz .LBB0_10
	s_ashr_i32 s3, s2, 31
	s_lshl_b64 s[8:9], s[2:3], 2
	v_readlane_b32 s10, v253, 0
	v_readlane_b32 s11, v253, 1
	s_add_u32 s8, s10, s8
	s_addc_u32 s9, s11, s9
	v_mov_b32_e32 v1, 0x3000
	v_mov_b32_e32 v2, s89
	global_store_dword v1, v2, s[8:9] offset:512 sc0 sc1

; __device__ __forceinline__ void p0_prep(const Params& p, LAS unsigned char* lds) {
;     ...
;     for (int i = blockIdx.x * 512 + threadIdx.x; i < (MPAD - MALL) * D / 8; i += gridDim.x * 512) ((u32x4*)(ws + OFF_XN16 + (size_t)MALL * D * 2))[i] = (u32x4){0u, 0u, 0u, 0u};
;     for (int i = blockIdx.x * 512 + threadIdx.x; i < 2 * MPAD; i += gridDim.x * 512) ((float*)(ws + OFF_SS1))[i] = 0.f;
;     if (blockIdx.x == 0 && threadIdx.x < 64) ((unsigned*)(ws + OFF_CNT))[threadIdx.x] = 0u;
.LBB0_15:
	v_ashrrev_i32_e32 v7, 31, v6
	v_lshl_add_u64 v[2:3], v[6:7], 2, s[4:5]
	v_add_u32_e32 v6, s3, v6
	v_cmp_lt_i32_e32 vcc, s28, v6
	s_or_b64 s[26:27], vcc, s[26:27]
	global_store_dword v[2:3], v1, off sc0 sc1
	s_andn2_b64 exec, exec, s[26:27]
	s_cbranch_execnz .LBB0_15
.LBB0_16:
	s_or_b64 exec, exec, s[0:1]
	v_cmp_gt_u32_e64 s[4:5], 64, v132
	s_and_b64 s[6:7], s[6:7], s[4:5]
	s_and_saveexec_b64 s[0:1], s[6:7]
	s_cbranch_execz .LBB0_18
	v_lshlrev_b32_e32 v2, 2, v132
	v_mov_b32_e32 v3, 0
	v_lshl_add_u64 v[4:5], s[82:83], 0, v[2:3]
	v_add_co_u32_e32 v4, vcc, 0x1b6e000, v4
	s_nop 1
	v_addc_co_u32_e32 v5, vcc, 0, v5, vcc
	global_store_dword v[4:5], v3, off offset:2048 sc0 sc1

; __global__ void __launch_bounds__(512, 2) hymba_fwd(Params p) {
;     ...
;     grid.sync();
.LBB0_62:
	s_or_b64 exec, exec, s[10:11]
	v_lshrrev_b32_e32 v1, 20, v0
	v_lshrrev_b32_e32 v0, 10, v0
	v_or_b32_e32 v0, v0, v1
	s_movk_i32 s0, 0x3ff
	v_and_or_b32 v0, v0, s0, v132
	v_cmp_eq_u32_e32 vcc, 0, v0
	s_waitcnt lgkmcnt(0)
	s_waitcnt vmcnt(0)
	s_barrier
	s_and_saveexec_b64 s[0:1], vcc
	s_cbranch_execz .LBB0_72
	s_load_dwordx2 s[6:7], s[24:25], 0x58
	v_mov_b32_e32 v2, 0
	v_readlane_b32 s8, v253, 0
	v_readlane_b32 s9, v253, 1
	s_and_b32 s10, s2, 7
	s_lshl_b32 s11, s10, 7
	s_addk_i32 s11, 0x3600
	v_mov_b32_e32 v4, s11
	s_waitcnt lgkmcnt(0)
	global_load_dword v0, v2, s[6:7] offset:32 sc1
	s_nop 0
	s_waitcnt vmcnt(0)
